# residual GEMM phases: split-K context unit runs before the full tile on workgroups that own one
# baseline (speedup 1.0000x reference)
.LBB0_196:
	s_cmp_lg_u32 s50, 2
	s_cselect_b64 s[10:11], -1, 0
	s_and_b64 s[10:11], s[28:29], s[10:11]
	s_and_b64 s[10:11], s[10:11], exec
	s_cselect_b32 s36, 0, 16
	s_cmp_eq_u32 s50, 6
	s_cselect_b64 s[18:19], -1, 0
	s_and_b64 s[10:11], s[18:19], exec
	s_movk_i32 s10, 0xb00
	s_cselect_b32 s13, 0x400, s10
	s_mov_b32 s10, 19
	s_cselect_b32 s51, 4, 11
	s_ashr_i32 s11, s10, 31
	s_lshr_b32 s35, s13, 6
	s_lshl_b64 s[10:11], s[10:11], 3
	s_add_u32 s10, s0, s10
	s_addc_u32 s11, s1, s11
	s_load_dwordx2 s[10:11], s[10:11], 0x0
	v_mov_b32_e32 v14, v224
	s_mov_b32 s42, 0
	s_mul_i32 s36, s36, s51
	s_mov_b64 s[14:15], -1
	v_readfirstlane_b32 s24, v14
	s_andn2_b64 vcc, exec, s[94:95]
	s_mov_b32 s61, s35
	s_mov_b32 s12, 0
	v_readlane_b32 s58, v249, 2
	v_readlane_b32 s43, v249, 1
	s_cbranch_vccnz .Lres_first_main
	v_readlane_b32 s12, v249, 0
	s_cmp_ge_u32 s12, s36
	s_mov_b64 s[14:15], 0
	s_cbranch_scc1 .LBB0_199
	v_cvt_f32_ubyte0_e32 v0, s51
	v_rcp_iflag_f32_e32 v2, v0
	v_readlane_b32 s16, v249, 0
	s_mov_b32 s42, 1
	s_mov_b32 s61, 4
	v_mul_f32_e32 v2, v227, v2
	v_trunc_f32_e32 v2, v2
	v_cvt_u32_f32_e32 v3, v2
	v_fma_f32 v2, -v2, v0, v227
	v_cmp_ge_f32_e64 s[14:15], |v2|, v0
	s_cmp_lg_u64 s[14:15], 0
	v_readfirstlane_b32 s12, v3
	s_addc_u32 s12, s12, 0
	s_and_b32 s14, s12, 0xff
	s_lshr_b32 s15, s12, 2
	s_mul_i32 s14, s51, s14
	s_or_b32 s15, s15, 64
	s_sub_i32 s14, s16, s14
	s_and_b32 s43, s15, 0x7f
	s_and_b32 s58, s12, 3
	s_lshl_b32 s12, s14, 2
	s_mov_b64 s[14:15], -1
	s_branch .LBB0_199
.Lres_first_main:
	s_cmpk_lg_i32 s46, 0x100
	s_cbranch_scc1 .LBB0_199
	s_cmp_ge_u32 s2, s36
	s_cbranch_scc1 .LBB0_199
	s_cmp_eq_u32 s51, 4
	s_cbranch_scc1 .Lres_div4
	s_mul_i32 s14, s2, 0x1746
	s_lshr_b32 s14, s14, 16
	s_branch .Lres_divdone
.Lres_div4:
	s_lshr_b32 s14, s2, 2
.Lres_divdone:
	s_mul_i32 s15, s14, s51
	s_sub_i32 s15, s2, s15
	s_lshl_b32 s12, s15, 2
	s_lshr_b32 s15, s14, 2
	s_add_i32 s43, s15, 64
	s_and_b32 s58, s14, 3
	s_mov_b32 s42, 1
	s_mov_b32 s61, 4
	s_mov_b64 s[14:15], -1

.LBB0_205:
	s_add_i32 s55, s55, 1
	s_mul_i32 s13, s55, s46
	s_add_i32 s13, s13, s2
	s_cmp_lg_u32 s55, 1
	s_cbranch_scc1 .Lres_noswap
	s_cmpk_lg_i32 s46, 0x100
	s_cbranch_scc1 .Lres_noswap
	s_cmp_ge_u32 s2, s36
	s_cbranch_scc1 .Lres_noswap
	s_mov_b32 s13, s2
.Lres_noswap:
	s_cmpk_gt_i32 s13, 0xff
	s_mov_b64 s[26:27], -1
	s_cbranch_scc0 .LBB0_208
	s_add_i32 s23, s13, 0xffffff00
	s_mov_b64 s[26:27], 0
	s_cmp_ge_i32 s23, s36
	s_mov_b64 s[24:25], 0
	s_cbranch_scc1 .LBB0_208
	s_mul_hi_u32 s22, s23, s56
	s_mul_i32 s24, s22, s51
	s_sub_i32 s24, s23, s24
	s_add_i32 s25, s22, 1
	s_sub_i32 s30, s24, s51
	s_cmp_ge_u32 s24, s51
	s_cselect_b32 s22, s25, s22
	s_cselect_b32 s24, s30, s24
	s_add_i32 s25, s22, 1
	s_cmp_ge_u32 s24, s51
	s_cselect_b32 s22, s25, s22
	s_mul_i32 s24, s22, s51
	s_sub_i32 s23, s23, s24
	s_lshr_b32 s24, s22, 2
	s_mov_b32 s57, 1
	s_add_i32 s47, s24, 64
	s_and_b32 s60, s22, 3
	s_lshl_b32 s22, s23, 2
	s_mov_b32 s59, 4
	s_mov_b64 s[24:25], -1
